# v053 + priority reset at K-loop exit so the tile epilogue runs at equal wave priority
# baseline (speedup 1.0000x reference)
; __device__ __forceinline__ void epilogue(const Params& p, int mode, int atomic, float alpha, const f32x4 (&acc)[2][2][4][2], int pm, int pn, int wr, int wc, int fr, int fq) {
;     ...
;     } else {
;         const bool isv = pn >= 2; const int c0 = (pn - (isv ? 2 : 0)) * 256;
;         float* dst = isv ? p.out + O_MVP : (float*)(p.ws + WS_MKRAW);
; #pragma unroll
;         for (int ai = 0; ai < 2; ++ai)
; #pragma unroll
;             for (int m = 0; m < 4; ++m) {
;                 const int row = row0 + ai * 128 + m * 16;
; #pragma unroll
;                 for (int bj = 0; bj < 2; ++bj) {
;                     *(f32x4*)(dst + (size_t)row * 512 + c0 + bj * 128 + cw) = acc[ai][bj][m][0];
;                     *(f32x4*)(dst + (size_t)row * 512 + c0 + bj * 128 + cw + 4) = acc[ai][bj][m][1];
;                 }
;             }
;     }
; __device__ __forceinline__ void gemm_phase(LAS unsigned char* lds, const Params& p, const Sched& S, float alpha, const int TIDX) {
;     ...
;         epilogue(p, cur.gid ? S.g1.mode : S.g0.mode, cur.atomic ? cur.part + 1 : 0, alpha, acc, cur.pm, cur.pn, wr, wc, fr, fq);
;         if (!has_next) break;
; #pragma unroll
;         for (int a = 0; a < 2; ++a)
; #pragma unroll
;             for (int b = 0; b < 2; ++b)
; #pragma unroll
;                 for (int m = 0; m < 4; ++m)
; #pragma unroll
;                     for (int n = 0; n < 2; ++n) acc[a][b][m][n] = (f32x4){0.f, 0.f, 0.f, 0.f};
;         cur = nxt; cA = nA; cB = nB; nt = cur.nt; ++ui;
.LBB0_291:
	s_setprio 0
	s_cmp_eq_u32 s0, 0
	s_cselect_b32 s0, s97, s28
	s_cmp_lg_u32 s0, 0
	v_lshl_add_u32 v154, s65, 8, v147
	s_cbranch_scc0 .LBB0_396
	s_add_i32 s3, s3, 1
	s_cmp_lg_u32 s64, 0
	s_cselect_b32 s48, s3, 0
	s_cmp_gt_u32 s0, 2
	s_cselect_b64 s[38:39], -1, 0
	s_cmp_eq_u32 s48, 0
	s_cselect_b64 s[6:7], -1, 0
	s_or_b64 s[50:51], s[6:7], s[38:39]
	v_readlane_b32 s52, v255, 20
	s_mov_b64 s[6:7], -1
	s_and_b64 vcc, exec, s[50:51]
	v_readlane_b32 s64, v255, 32
	v_readlane_b32 s65, v255, 33
	v_readlane_b32 s66, v255, 34
	v_readlane_b32 s67, v255, 35
	v_readlane_b32 s53, v255, 21
	v_readlane_b32 s54, v255, 22
	v_readlane_b32 s55, v255, 23
	v_readlane_b32 s56, v255, 24
	v_readlane_b32 s57, v255, 25
	v_readlane_b32 s58, v255, 26
	v_readlane_b32 s59, v255, 27
	v_readlane_b32 s60, v255, 28
	v_readlane_b32 s61, v255, 29
	v_readlane_b32 s62, v255, 30
	v_readlane_b32 s63, v255, 31
	s_cbranch_vccz .LBB0_393
	s_mov_b64 s[52:53], s[64:65]
	s_and_b64 vcc, exec, s[38:39]
	s_mov_b64 s[54:55], s[66:67]
	s_cbranch_vccz .LBB0_326
	s_cmp_lg_u32 s0, 3
	s_cbranch_scc0 .LBB0_296
	s_cmp_gt_i32 s26, 1
	v_readlane_b32 s6, v255, 40
	v_readlane_b32 s7, v255, 42
	s_cselect_b32 s3, -2, 0
	s_cselect_b32 s38, s6, s7
	v_readlane_b32 s6, v255, 39
	v_readlane_b32 s7, v255, 41
	s_cselect_b32 s39, s6, s7
	s_add_i32 s3, s3, s26
	s_lshl_b32 s6, s3, 8
	s_ashr_i32 s7, s6, 31
	s_lshl_b64 s[6:7], s[6:7], 2
	s_add_u32 s6, s39, s6
	v_or_b32_e32 v134, 16, v154
	s_addc_u32 s7, s38, s7
	v_lshlrev_b32_e32 v0, 2, v146
	v_ashrrev_i32_e32 v155, 31, v154
	v_ashrrev_i32_e32 v135, 31, v134
	v_lshl_add_u64 v[130:131], s[6:7], 0, v[0:1]
	v_lshlrev_b64 v[132:133], 11, v[154:155]
	v_lshlrev_b64 v[134:135], 11, v[134:135]
	v_lshl_add_u64 v[132:133], v[130:131], 0, v[132:133]
	v_lshl_add_u64 v[134:135], v[130:131], 0, v[134:135]
	global_store_dwordx4 v[132:133], v[126:129], off
	global_store_dwordx4 v[132:133], v[118:121], off offset:16
	global_store_dwordx4 v[132:133], v[122:125], off offset:512
	global_store_dwordx4 v[132:133], v[114:117], off offset:528
	global_store_dwordx4 v[134:135], v[110:113], off
	global_store_dwordx4 v[134:135], v[102:105], off offset:16
	global_store_dwordx4 v[134:135], v[106:109], off offset:512
	global_store_dwordx4 v[134:135], v[98:101], off offset:528
	v_or_b32_e32 v134, 32, v154
	v_ashrrev_i32_e32 v135, 31, v134
	v_lshlrev_b64 v[134:135], 11, v[134:135]
	v_lshl_add_u64 v[134:135], v[130:131], 0, v[134:135]
	global_store_dwordx4 v[134:135], v[94:97], off
	global_store_dwordx4 v[134:135], v[86:89], off offset:16
	global_store_dwordx4 v[134:135], v[90:93], off offset:512
	global_store_dwordx4 v[134:135], v[82:85], off offset:528
	v_or_b32_e32 v134, 48, v154
	v_ashrrev_i32_e32 v135, 31, v134
	v_lshlrev_b64 v[134:135], 11, v[134:135]
	v_lshl_add_u64 v[130:131], v[130:131], 0, v[134:135]
	v_add_co_u32_e32 v134, vcc, s77, v132
	s_mov_b64 s[6:7], 0x40000
	s_nop 0
	v_addc_co_u32_e32 v135, vcc, 0, v133, vcc
	s_mov_b32 s3, 0x48000
	global_store_dwordx4 v[130:131], v[78:81], off
	global_store_dwordx4 v[130:131], v[70:73], off offset:16
	global_store_dwordx4 v[130:131], v[74:77], off offset:512
	global_store_dwordx4 v[130:131], v[66:69], off offset:528
	v_lshl_add_u64 v[130:131], v[132:133], 0, s[6:7]
	global_store_dwordx4 v[134:135], v[62:65], off
	global_store_dwordx4 v[130:131], v[54:57], off offset:16
	global_store_dwordx4 v[130:131], v[58:61], off offset:512
	global_store_dwordx4 v[130:131], v[50:53], off offset:528
	v_add_co_u32_e32 v134, vcc, s3, v132
	s_mov_b64 s[6:7], 0x48000
	s_nop 0
	v_addc_co_u32_e32 v135, vcc, 0, v133, vcc
	v_lshl_add_u64 v[130:131], v[132:133], 0, s[6:7]
	global_store_dwordx4 v[134:135], v[46:49], off
	global_store_dwordx4 v[130:131], v[38:41], off offset:16
	global_store_dwordx4 v[130:131], v[42:45], off offset:512
	global_store_dwordx4 v[130:131], v[34:37], off offset:528
	s_mov_b64 s[6:7], 0x50000
	v_add_co_u32_e32 v134, vcc, s33, v132
	v_lshl_add_u64 v[130:131], v[132:133], 0, s[6:7]
	s_nop 0
	v_addc_co_u32_e32 v135, vcc, 0, v133, vcc
	s_mov_b64 s[6:7], 0x58000
	global_store_dwordx4 v[134:135], v[30:33], off
	global_store_dwordx4 v[130:131], v[22:25], off offset:16
	global_store_dwordx4 v[130:131], v[26:29], off offset:512
	global_store_dwordx4 v[130:131], v[18:21], off offset:528
	v_lshl_add_u64 v[130:131], v[132:133], 0, s[6:7]
	v_add_co_u32_e32 v132, vcc, 0x58000, v132
	s_mov_b64 s[6:7], 0
	s_nop 0
	v_addc_co_u32_e32 v133, vcc, 0, v133, vcc
	global_store_dwordx4 v[132:133], v[14:17], off
	global_store_dwordx4 v[130:131], v[6:9], off offset:16
	global_store_dwordx4 v[130:131], v[10:13], off offset:512
	global_store_dwordx4 v[130:131], v[2:5], off offset:528
